# GDN right-hand sides: LDS reads software-pipelined two time steps ahead
# baseline (speedup 1.0000x reference)
; #define LAS __attribute__((address_space(3)))
; #define LDS_WAIT() asm volatile("s_waitcnt lgkmcnt(0)" ::: "memory")
; DI void gdn_scan_block(LAS unsigned char* lds, int c, const float* P, const GdnPar& pr, float* ORAW, int tid, int lane, int wave) {
;     ...
;         if (wave < 4) {
;             const int cw16 = 16 * wave;
; #pragma unroll
;             for (int tb = 0; tb < 2; ++tb)
; #pragma unroll
;                 for (int i = 0; i < 4; ++i) { const int t = 16 * tb + 4 * g + i;
;                     RH[t * 64 + cw16 + m] = AB_[2 * t + 1] * (V_[t * 64 + cw16 + m] - __expf(GC_[t]) * P0a[tb][i]); }
;             LDS_WAIT(); asm volatile("" ::: "memory");
;             if (lane < 16) {
;                 float cc[32];
;                 const int rowi = cw16 + lane;
; #pragma unroll
;                 for (int tb8 = 0; tb8 < 4; ++tb8) {
;                     float acc[8];
; #pragma unroll
;                     for (int r = 0; r < 8; ++r) acc[r] = RH[(8 * tb8 + r) * 64 + rowi];
; #pragma unroll
;                     for (int jb = 0; jb < tb8; ++jb)
; #pragma unroll
;                         for (int r = 0; r < 8; ++r) { const f32x4 b0 = *(const LAS f32x4*)(BM + (8 * tb8 + r) * 32 + 8 * jb), b1 = *(const LAS f32x4*)(BM + (8 * tb8 + r) * 32 + 8 * jb + 4);
;                             acc[r] -= ((b0[0] * cc[8 * jb] + b0[1] * cc[8 * jb + 1]) + (b0[2] * cc[8 * jb + 2] + b0[3] * cc[8 * jb + 3])) + ((b1[0] * cc[8 * jb + 4] + b1[1] * cc[8 * jb + 5]) + (b1[2] * cc[8 * jb + 6] + b1[3] * cc[8 * jb + 7])); }
; #pragma unroll
;                     for (int rh = 0; rh < 2; ++rh) {
;                         f32x4 d0[4], d1[4];
; #pragma unroll
;                         for (int r = 0; r < 4; ++r) { d0[r] = *(const LAS f32x4*)(BM + (8 * tb8 + 4 * rh + r) * 32 + 8 * tb8); if (rh) d1[r] = *(const LAS f32x4*)(BM + (8 * tb8 + 4 * rh + r) * 32 + 8 * tb8 + 4); }
; #pragma unroll
;                         for (int r = 0; r < 4; ++r) { float av = acc[4 * rh + r];
; #pragma unroll
;                             for (int q = 0; q < 8; ++q) if (q < 4 * rh + r) av -= (q < 4 ? d0[r][q & 3] : d1[r][q & 3]) * cc[8 * tb8 + q];
;                             cc[8 * tb8 + 4 * rh + r] = av; CC[(8 * tb8 + 4 * rh + r) * 64 + rowi] = av; }
.LBB0_912:
	s_or_b64 exec, exec, s[34:35]
	ds_write_b32 v188, v72 offset:55040
	s_waitcnt lgkmcnt(0)
	s_barrier
	s_and_b64 vcc, exec, s[94:95]
	s_cbranch_vccz .LBB0_889
	ds_read_b32 v189, v178 offset:42240
	ds_read_b32 v190, v140 offset:33792
	ds_read_b32 v191, v139 offset:41988
	ds_read_b32 v192, v178 offset:42244
	ds_read_b32 v193, v141 offset:33792
	ds_read_b32 v194, v179 offset:41988
	ds_read_b32 v195, v178 offset:42248
	ds_read_b32 v196, v142 offset:33792
	ds_read_b32 v197, v180 offset:41988
	s_waitcnt lgkmcnt(6)
	v_mul_f32_e32 v189, 0x3fb8aa3b, v189
	v_exp_f32_e32 v189, v189
	s_nop 0
	v_fma_f32 v72, -v56, v189, v190
	v_mul_f32_e32 v72, v191, v72
	ds_write_b32 v140, v72 offset:59264
	ds_read_b32 v189, v178 offset:42252
	ds_read_b32 v190, v143 offset:33792
	ds_read_b32 v191, v181 offset:41988
	s_waitcnt lgkmcnt(7)
	v_mul_f32_e32 v192, 0x3fb8aa3b, v192
	v_exp_f32_e32 v192, v192
	s_nop 0
	v_fma_f32 v72, -v57, v192, v193
	v_mul_f32_e32 v72, v194, v72
	ds_write_b32 v141, v72 offset:59264
	ds_read_b32 v192, v178 offset:42304
	ds_read_b32 v193, v144 offset:33792
	ds_read_b32 v194, v182 offset:41988
	s_waitcnt lgkmcnt(8)
	v_mul_f32_e32 v195, 0x3fb8aa3b, v195
	v_exp_f32_e32 v195, v195
	s_nop 0
	v_fma_f32 v72, -v58, v195, v196
	v_mul_f32_e32 v72, v197, v72
	ds_write_b32 v142, v72 offset:59264
	ds_read_b32 v195, v178 offset:42308
	ds_read_b32 v196, v145 offset:33792
	ds_read_b32 v197, v183 offset:41988
	s_waitcnt lgkmcnt(8)
	v_mul_f32_e32 v189, 0x3fb8aa3b, v189
	v_exp_f32_e32 v189, v189
	s_nop 0
	v_fma_f32 v72, -v59, v189, v190
	v_mul_f32_e32 v72, v191, v72
	ds_write_b32 v143, v72 offset:59264
	ds_read_b32 v189, v178 offset:42312
	ds_read_b32 v190, v146 offset:33792
	ds_read_b32 v191, v184 offset:41988
	s_waitcnt lgkmcnt(8)
	v_mul_f32_e32 v192, 0x3fb8aa3b, v192
	v_exp_f32_e32 v192, v192
	s_nop 0
	v_fma_f32 v72, -v60, v192, v193
	v_mul_f32_e32 v72, v194, v72
	ds_write_b32 v144, v72 offset:59264
	ds_read_b32 v192, v178 offset:42316
	ds_read_b32 v193, v147 offset:33792
	ds_read_b32 v194, v185 offset:41988
	s_waitcnt lgkmcnt(8)
	v_mul_f32_e32 v195, 0x3fb8aa3b, v195
	v_exp_f32_e32 v195, v195
	s_nop 0
	v_fma_f32 v72, -v61, v195, v196
	v_mul_f32_e32 v72, v197, v72
	ds_write_b32 v145, v72 offset:59264
	s_waitcnt lgkmcnt(5)
	v_mul_f32_e32 v189, 0x3fb8aa3b, v189
	v_exp_f32_e32 v189, v189
	s_nop 0
	v_fma_f32 v72, -v62, v189, v190
	v_mul_f32_e32 v72, v191, v72
	ds_write_b32 v146, v72 offset:59264
	s_waitcnt lgkmcnt(2)
	v_mul_f32_e32 v192, 0x3fb8aa3b, v192
	v_exp_f32_e32 v192, v192
	s_nop 0
	v_fma_f32 v72, -v63, v192, v193
	v_mul_f32_e32 v72, v194, v72
	ds_write_b32 v147, v72 offset:59264
	s_waitcnt lgkmcnt(0)
	s_and_saveexec_b64 s[34:35], s[8:9]
	s_cbranch_execz .LBB0_888
	v_mov_b32_e32 v128, s78
	ds_read2st64_b32 v[80:81], v132 offset0:0 offset1:1
	ds_read2st64_b32 v[104:105], v132 offset0:2 offset1:3
	ds_read_b128 v[72:75], v128 offset:51072
	ds_read_b128 v[76:79], v128 offset:51200
	ds_read_b128 v[100:103], v128 offset:51328
	ds_read_b128 v[208:211], v128 offset:51456
	s_waitcnt lgkmcnt(3)
	v_mov_b32_e32 v189, v80
	v_fma_f32 v190, -v72, v189, v81
	ds_read_b128 v[212:215], v128 offset:51584
	ds_write2st64_b32 v133, v189, v190 offset0:0 offset1:1
	ds_read2st64_b32 v[130:131], v132 offset0:4 offset1:5
	s_waitcnt lgkmcnt(4)
	v_fma_f32 v104, -v76, v189, v104
	v_fma_f32 v105, -v100, v189, v105
	v_fma_f32 v191, -v77, v190, v104
	v_fma_f32 v105, -v101, v190, v105
	v_fma_f32 v192, -v102, v191, v105
	ds_read_b128 v[72:75], v128 offset:51600
	ds_read_b128 v[76:79], v128 offset:51712
	ds_write2st64_b32 v133, v191, v192 offset0:2 offset1:3
	ds_read2st64_b32 v[80:81], v132 offset0:6 offset1:7
	s_waitcnt lgkmcnt(4)
	v_fma_f32 v130, -v208, v189, v130
	v_fma_f32 v131, -v212, v189, v131
	v_fma_f32 v130, -v209, v190, v130
	v_fma_f32 v131, -v213, v190, v131
	v_fma_f32 v130, -v210, v191, v130
	v_fma_f32 v131, -v214, v191, v131
	v_fma_f32 v193, -v211, v192, v130
	v_fma_f32 v131, -v215, v192, v131
	ds_read_b128 v[100:103], v128 offset:51840
	ds_read_b128 v[208:211], v128 offset:51728
	s_waitcnt lgkmcnt(5)
	v_fma_f32 v194, -v72, v193, v131
	ds_read_b128 v[212:215], v128 offset:51856
	ds_write2st64_b32 v133, v193, v194 offset0:4 offset1:5
	ds_read2st64_b32 v[104:105], v132 offset0:8 offset1:9
	s_waitcnt lgkmcnt(4)
	v_fma_f32 v80, -v76, v189, v80
	v_fma_f32 v81, -v100, v189, v81
	v_fma_f32 v80, -v77, v190, v80
	v_fma_f32 v81, -v101, v190, v81
	v_fma_f32 v80, -v78, v191, v80
	v_fma_f32 v81, -v102, v191, v81
	v_fma_f32 v80, -v79, v192, v80
	v_fma_f32 v81, -v103, v192, v81
	ds_read_b128 v[72:75], v128 offset:51968
	ds_read_b128 v[76:79], v128 offset:52096
	s_waitcnt lgkmcnt(4)
	v_fma_f32 v80, -v208, v193, v80
	v_fma_f32 v81, -v212, v193, v81
	v_fma_f32 v195, -v209, v194, v80
	v_fma_f32 v81, -v213, v194, v81
	v_fma_f32 v196, -v214, v195, v81
	ds_read_b128 v[100:103], v128 offset:51984
	ds_read_b128 v[208:211], v128 offset:52112
	ds_write2st64_b32 v133, v195, v196 offset0:6 offset1:7
	ds_read2st64_b32 v[130:131], v132 offset0:10 offset1:11
	s_waitcnt lgkmcnt(4)
	v_fma_f32 v104, -v72, v189, v104
	v_fma_f32 v105, -v76, v189, v105
	v_fma_f32 v104, -v73, v190, v104
	v_fma_f32 v105, -v77, v190, v105
	v_fma_f32 v104, -v74, v191, v104
	v_fma_f32 v105, -v78, v191, v105
	v_fma_f32 v104, -v75, v192, v104
	v_fma_f32 v105, -v79, v192, v105
	ds_read_b128 v[212:215], v128 offset:52128
	ds_read_b128 v[72:75], v128 offset:52224
	s_waitcnt lgkmcnt(4)
	v_fma_f32 v104, -v100, v193, v104
	v_fma_f32 v105, -v208, v193, v105
	v_fma_f32 v104, -v101, v194, v104
	v_fma_f32 v105, -v209, v194, v105
	v_fma_f32 v104, -v102, v195, v104
	v_fma_f32 v105, -v210, v195, v105
	v_fma_f32 v197, -v103, v196, v104
	v_fma_f32 v105, -v211, v196, v105
	ds_read_b128 v[76:79], v128 offset:52352
	ds_read_b128 v[100:103], v128 offset:52240
	s_waitcnt lgkmcnt(3)
; #define LAS __attribute__((address_space(3)))
; DI void gdn_scan_block(LAS unsigned char* lds, int c, const float* P, const GdnPar& pr, float* ORAW, int tid, int lane, int wave) {
;     ...
;                 for (int tb8 = 0; tb8 < 4; ++tb8) {
;                     float acc[8];
; #pragma unroll
;                     for (int r = 0; r < 8; ++r) acc[r] = RH[(8 * tb8 + r) * 64 + rowi];
; #pragma unroll
;                     for (int jb = 0; jb < tb8; ++jb)
; #pragma unroll
;                         for (int r = 0; r < 8; ++r) { const f32x4 b0 = *(const LAS f32x4*)(BM + (8 * tb8 + r) * 32 + 8 * jb), b1 = *(const LAS f32x4*)(BM + (8 * tb8 + r) * 32 + 8 * jb + 4);
;                             acc[r] -= ((b0[0] * cc[8 * jb] + b0[1] * cc[8 * jb + 1]) + (b0[2] * cc[8 * jb + 2] + b0[3] * cc[8 * jb + 3])) + ((b1[0] * cc[8 * jb + 4] + b1[1] * cc[8 * jb + 5]) + (b1[2] * cc[8 * jb + 6] + b1[3] * cc[8 * jb + 7])); }
; #pragma unroll
;                     for (int rh = 0; rh < 2; ++rh) {
;                         f32x4 d0[4], d1[4];
; #pragma unroll
;                         for (int r = 0; r < 4; ++r) { d0[r] = *(const LAS f32x4*)(BM + (8 * tb8 + 4 * rh + r) * 32 + 8 * tb8); if (rh) d1[r] = *(const LAS f32x4*)(BM + (8 * tb8 + 4 * rh + r) * 32 + 8 * tb8 + 4); }
; #pragma unroll
;                         for (int r = 0; r < 4; ++r) { float av = acc[4 * rh + r];
; #pragma unroll
;                             for (int q = 0; q < 8; ++q) if (q < 4 * rh + r) av -= (q < 4 ? d0[r][q & 3] : d1[r][q & 3]) * cc[8 * tb8 + q];
;                             cc[8 * tb8 + 4 * rh + r] = av; CC[(8 * tb8 + 4 * rh + r) * 64 + rowi] = av; }
	v_fma_f32 v198, -v212, v197, v105
	ds_read_b128 v[208:211], v128 offset:52368
	ds_write2st64_b32 v133, v197, v198 offset0:8 offset1:9
	ds_read2st64_b32 v[80:81], v132 offset0:12 offset1:13
	s_waitcnt lgkmcnt(4)
	v_fma_f32 v130, -v72, v189, v130
	v_fma_f32 v131, -v76, v189, v131
	v_fma_f32 v130, -v73, v190, v130
	v_fma_f32 v131, -v77, v190, v131
	v_fma_f32 v130, -v74, v191, v130
	v_fma_f32 v131, -v78, v191, v131
	v_fma_f32 v130, -v75, v192, v130
	v_fma_f32 v131, -v79, v192, v131
	ds_read_b128 v[212:215], v128 offset:52256
	ds_read_b128 v[72:75], v128 offset:52384
	s_waitcnt lgkmcnt(4)
	v_fma_f32 v130, -v100, v193, v130
	v_fma_f32 v131, -v208, v193, v131
	v_fma_f32 v130, -v101, v194, v130
	v_fma_f32 v131, -v209, v194, v131
	v_fma_f32 v130, -v102, v195, v130
	v_fma_f32 v131, -v210, v195, v131
	v_fma_f32 v130, -v103, v196, v130
	v_fma_f32 v131, -v211, v196, v131
	ds_read_b128 v[76:79], v128 offset:52480
	ds_read_b128 v[100:103], v128 offset:52608
	s_waitcnt lgkmcnt(2)
	v_fma_f32 v130, -v212, v197, v130
	v_fma_f32 v131, -v72, v197, v131
	v_fma_f32 v199, -v213, v198, v130
	v_fma_f32 v131, -v73, v198, v131
	v_fma_f32 v200, -v74, v199, v131
	ds_read_b128 v[208:211], v128 offset:52496
	ds_read_b128 v[212:215], v128 offset:52624
	ds_write2st64_b32 v133, v199, v200 offset0:10 offset1:11
	ds_read2st64_b32 v[104:105], v132 offset0:14 offset1:15
	s_waitcnt lgkmcnt(4)
	v_fma_f32 v80, -v76, v189, v80
	v_fma_f32 v81, -v100, v189, v81
	v_fma_f32 v80, -v77, v190, v80
	v_fma_f32 v81, -v101, v190, v81
	v_fma_f32 v80, -v78, v191, v80
	v_fma_f32 v81, -v102, v191, v81
	v_fma_f32 v80, -v79, v192, v80
	v_fma_f32 v81, -v103, v192, v81
	ds_read_b128 v[72:75], v128 offset:52512
	ds_read_b128 v[76:79], v128 offset:52640
	s_waitcnt lgkmcnt(4)
	v_fma_f32 v80, -v208, v193, v80
	v_fma_f32 v81, -v212, v193, v81
	v_fma_f32 v80, -v209, v194, v80
	v_fma_f32 v81, -v213, v194, v81
	v_fma_f32 v80, -v210, v195, v80
	v_fma_f32 v81, -v214, v195, v81
	v_fma_f32 v80, -v211, v196, v80
	v_fma_f32 v81, -v215, v196, v81
	ds_read_b128 v[100:103], v128 offset:52656
	ds_read_b128 v[208:211], v128 offset:52736
	s_waitcnt lgkmcnt(2)
	v_fma_f32 v80, -v72, v197, v80
	v_fma_f32 v81, -v76, v197, v81
	v_fma_f32 v80, -v73, v198, v80
	v_fma_f32 v81, -v77, v198, v81
	v_fma_f32 v80, -v74, v199, v80
	v_fma_f32 v81, -v78, v199, v81
	v_fma_f32 v201, -v75, v200, v80
	v_fma_f32 v81, -v79, v200, v81
	ds_read_b128 v[212:215], v128 offset:52864
	ds_read_b128 v[72:75], v128 offset:52752
	s_waitcnt lgkmcnt(3)
	v_fma_f32 v202, -v100, v201, v81
	ds_read_b128 v[76:79], v128 offset:52880
	ds_write2st64_b32 v133, v201, v202 offset0:12 offset1:13
	ds_read2st64_b32 v[130:131], v132 offset0:16 offset1:17
	s_waitcnt lgkmcnt(4)
	v_fma_f32 v104, -v208, v189, v104
	v_fma_f32 v105, -v212, v189, v105
	v_fma_f32 v104, -v209, v190, v104
	v_fma_f32 v105, -v213, v190, v105
	v_fma_f32 v104, -v210, v191, v104
	v_fma_f32 v105, -v214, v191, v105
	v_fma_f32 v104, -v211, v192, v104
	v_fma_f32 v105, -v215, v192, v105
	ds_read_b128 v[100:103], v128 offset:52768
	ds_read_b128 v[208:211], v128 offset:52896
	s_waitcnt lgkmcnt(4)
	v_fma_f32 v104, -v72, v193, v104
	v_fma_f32 v105, -v76, v193, v105
	v_fma_f32 v104, -v73, v194, v104
	v_fma_f32 v105, -v77, v194, v105
	v_fma_f32 v104, -v74, v195, v104
	v_fma_f32 v105, -v78, v195, v105
	v_fma_f32 v104, -v75, v196, v104
	v_fma_f32 v105, -v79, v196, v105
	ds_read_b128 v[212:215], v128 offset:52784
	ds_read_b128 v[72:75], v128 offset:52912
	s_waitcnt lgkmcnt(2)
	v_fma_f32 v104, -v100, v197, v104
	v_fma_f32 v105, -v208, v197, v105
	v_fma_f32 v104, -v101, v198, v104
	v_fma_f32 v105, -v209, v198, v105
	v_fma_f32 v104, -v102, v199, v104
	v_fma_f32 v105, -v210, v199, v105
	v_fma_f32 v104, -v103, v200, v104
	v_fma_f32 v105, -v211, v200, v105
	ds_read_b128 v[76:79], v128 offset:52992
	ds_read_b128 v[100:103], v128 offset:53120
	s_waitcnt lgkmcnt(2)
	v_fma_f32 v104, -v212, v201, v104
	v_fma_f32 v105, -v72, v201, v105
	v_fma_f32 v203, -v213, v202, v104
	v_fma_f32 v105, -v73, v202, v105
	v_fma_f32 v204, -v74, v203, v105
	ds_read_b128 v[208:211], v128 offset:53008
	ds_read_b128 v[212:215], v128 offset:53136
	ds_write2st64_b32 v133, v203, v204 offset0:14 offset1:15
	ds_read2st64_b32 v[80:81], v132 offset0:18 offset1:19
	s_waitcnt lgkmcnt(4)
	v_fma_f32 v130, -v76, v189, v130
	v_fma_f32 v131, -v100, v189, v131
	v_fma_f32 v130, -v77, v190, v130
	v_fma_f32 v131, -v101, v190, v131
	v_fma_f32 v130, -v78, v191, v130
	v_fma_f32 v131, -v102, v191, v131
	v_fma_f32 v130, -v79, v192, v130
	v_fma_f32 v131, -v103, v192, v131
	ds_read_b128 v[72:75], v128 offset:53024
	ds_read_b128 v[76:79], v128 offset:53152
	s_waitcnt lgkmcnt(4)
	v_fma_f32 v130, -v208, v193, v130
	v_fma_f32 v131, -v212, v193, v131
	v_fma_f32 v130, -v209, v194, v130
	v_fma_f32 v131, -v213, v194, v131
	v_fma_f32 v130, -v210, v195, v130
	v_fma_f32 v131, -v214, v195, v131
	v_fma_f32 v130, -v211, v196, v130
	v_fma_f32 v131, -v215, v196, v131
	ds_read_b128 v[100:103], v128 offset:53040
	ds_read_b128 v[208:211], v128 offset:53168
	s_waitcnt lgkmcnt(2)
	v_fma_f32 v130, -v72, v197, v130
	v_fma_f32 v131, -v76, v197, v131
	v_fma_f32 v130, -v73, v198, v130
	v_fma_f32 v131, -v77, v198, v131
	v_fma_f32 v130, -v74, v199, v130
	v_fma_f32 v131, -v78, v199, v131
	v_fma_f32 v130, -v75, v200, v130
	v_fma_f32 v131, -v79, v200, v131
	ds_read_b128 v[212:215], v128 offset:53184
	ds_read_b128 v[72:75], v128 offset:53248
	s_waitcnt lgkmcnt(2)
	v_fma_f32 v130, -v100, v201, v130
	v_fma_f32 v131, -v208, v201, v131
	v_fma_f32 v130, -v101, v202, v130
	v_fma_f32 v131, -v209, v202, v131
	v_fma_f32 v130, -v102, v203, v130
	v_fma_f32 v131, -v210, v203, v131
	v_fma_f32 v205, -v103, v204, v130
	v_fma_f32 v131, -v211, v204, v131
	ds_read_b128 v[76:79], v128 offset:53376
	ds_read_b128 v[100:103], v128 offset:53264
	s_waitcnt lgkmcnt(3)
; #define LAS __attribute__((address_space(3)))
; DI void gdn_scan_block(LAS unsigned char* lds, int c, const float* P, const GdnPar& pr, float* ORAW, int tid, int lane, int wave) {
;     ...
;                 for (int tb8 = 0; tb8 < 4; ++tb8) {
;                     float acc[8];
; #pragma unroll
;                     for (int r = 0; r < 8; ++r) acc[r] = RH[(8 * tb8 + r) * 64 + rowi];
; #pragma unroll
;                     for (int jb = 0; jb < tb8; ++jb)
; #pragma unroll
;                         for (int r = 0; r < 8; ++r) { const f32x4 b0 = *(const LAS f32x4*)(BM + (8 * tb8 + r) * 32 + 8 * jb), b1 = *(const LAS f32x4*)(BM + (8 * tb8 + r) * 32 + 8 * jb + 4);
;                             acc[r] -= ((b0[0] * cc[8 * jb] + b0[1] * cc[8 * jb + 1]) + (b0[2] * cc[8 * jb + 2] + b0[3] * cc[8 * jb + 3])) + ((b1[0] * cc[8 * jb + 4] + b1[1] * cc[8 * jb + 5]) + (b1[2] * cc[8 * jb + 6] + b1[3] * cc[8 * jb + 7])); }
; #pragma unroll
;                     for (int rh = 0; rh < 2; ++rh) {
;                         f32x4 d0[4], d1[4];
; #pragma unroll
;                         for (int r = 0; r < 4; ++r) { d0[r] = *(const LAS f32x4*)(BM + (8 * tb8 + 4 * rh + r) * 32 + 8 * tb8); if (rh) d1[r] = *(const LAS f32x4*)(BM + (8 * tb8 + 4 * rh + r) * 32 + 8 * tb8 + 4); }
; #pragma unroll
;                         for (int r = 0; r < 4; ++r) { float av = acc[4 * rh + r];
; #pragma unroll
;                             for (int q = 0; q < 8; ++q) if (q < 4 * rh + r) av -= (q < 4 ? d0[r][q & 3] : d1[r][q & 3]) * cc[8 * tb8 + q];
;                             cc[8 * tb8 + 4 * rh + r] = av; CC[(8 * tb8 + 4 * rh + r) * 64 + rowi] = av; }
	v_fma_f32 v216, -v212, v205, v131
	ds_read_b128 v[208:211], v128 offset:53392
	ds_write2st64_b32 v133, v205, v216 offset0:16 offset1:17
	ds_read2st64_b32 v[104:105], v132 offset0:20 offset1:21
	s_waitcnt lgkmcnt(4)
	v_fma_f32 v80, -v72, v189, v80
	v_fma_f32 v81, -v76, v189, v81
	v_fma_f32 v80, -v73, v190, v80
	v_fma_f32 v81, -v77, v190, v81
	v_fma_f32 v80, -v74, v191, v80
	v_fma_f32 v81, -v78, v191, v81
	v_fma_f32 v80, -v75, v192, v80
	v_fma_f32 v81, -v79, v192, v81
	ds_read_b128 v[212:215], v128 offset:53280
	ds_read_b128 v[72:75], v128 offset:53408
	s_waitcnt lgkmcnt(4)
	v_fma_f32 v80, -v100, v193, v80
	v_fma_f32 v81, -v208, v193, v81
	v_fma_f32 v80, -v101, v194, v80
	v_fma_f32 v81, -v209, v194, v81
	v_fma_f32 v80, -v102, v195, v80
	v_fma_f32 v81, -v210, v195, v81
	v_fma_f32 v80, -v103, v196, v80
	v_fma_f32 v81, -v211, v196, v81
	ds_read_b128 v[76:79], v128 offset:53296
	ds_read_b128 v[100:103], v128 offset:53424
	s_waitcnt lgkmcnt(2)
	v_fma_f32 v80, -v212, v197, v80
	v_fma_f32 v81, -v72, v197, v81
	v_fma_f32 v80, -v213, v198, v80
	v_fma_f32 v81, -v73, v198, v81
	v_fma_f32 v80, -v214, v199, v80
	v_fma_f32 v81, -v74, v199, v81
	v_fma_f32 v80, -v215, v200, v80
	v_fma_f32 v81, -v75, v200, v81
	ds_read_b128 v[208:211], v128 offset:53312
	ds_read_b128 v[212:215], v128 offset:53440
	s_waitcnt lgkmcnt(2)
	v_fma_f32 v80, -v76, v201, v80
	v_fma_f32 v81, -v100, v201, v81
	v_fma_f32 v80, -v77, v202, v80
	v_fma_f32 v81, -v101, v202, v81
	v_fma_f32 v80, -v78, v203, v80
	v_fma_f32 v81, -v102, v203, v81
	v_fma_f32 v80, -v79, v204, v80
	v_fma_f32 v81, -v103, v204, v81
	ds_read_b128 v[72:75], v128 offset:53504
	ds_read_b128 v[76:79], v128 offset:53632
	s_waitcnt lgkmcnt(2)
	v_fma_f32 v80, -v208, v205, v80
	v_fma_f32 v81, -v212, v205, v81
	v_fma_f32 v217, -v209, v216, v80
	v_fma_f32 v81, -v213, v216, v81
	v_fma_f32 v218, -v214, v217, v81
	ds_read_b128 v[100:103], v128 offset:53520
	ds_read_b128 v[208:211], v128 offset:53648
	ds_write2st64_b32 v133, v217, v218 offset0:18 offset1:19
	ds_read2st64_b32 v[130:131], v132 offset0:22 offset1:23
	s_waitcnt lgkmcnt(4)
	v_fma_f32 v104, -v72, v189, v104
	v_fma_f32 v105, -v76, v189, v105
	v_fma_f32 v104, -v73, v190, v104
	v_fma_f32 v105, -v77, v190, v105
	v_fma_f32 v104, -v74, v191, v104
	v_fma_f32 v105, -v78, v191, v105
	v_fma_f32 v104, -v75, v192, v104
	v_fma_f32 v105, -v79, v192, v105
	ds_read_b128 v[212:215], v128 offset:53536
	ds_read_b128 v[72:75], v128 offset:53664
	s_waitcnt lgkmcnt(4)
	v_fma_f32 v104, -v100, v193, v104
	v_fma_f32 v105, -v208, v193, v105
	v_fma_f32 v104, -v101, v194, v104
	v_fma_f32 v105, -v209, v194, v105
	v_fma_f32 v104, -v102, v195, v104
	v_fma_f32 v105, -v210, v195, v105
	v_fma_f32 v104, -v103, v196, v104
	v_fma_f32 v105, -v211, v196, v105
	ds_read_b128 v[76:79], v128 offset:53552
	ds_read_b128 v[100:103], v128 offset:53680
	s_waitcnt lgkmcnt(2)
	v_fma_f32 v104, -v212, v197, v104
	v_fma_f32 v105, -v72, v197, v105
	v_fma_f32 v104, -v213, v198, v104
	v_fma_f32 v105, -v73, v198, v105
	v_fma_f32 v104, -v214, v199, v104
	v_fma_f32 v105, -v74, v199, v105
	v_fma_f32 v104, -v215, v200, v104
	v_fma_f32 v105, -v75, v200, v105
	ds_read_b128 v[208:211], v128 offset:53568
	ds_read_b128 v[212:215], v128 offset:53696
	s_waitcnt lgkmcnt(2)
	v_fma_f32 v104, -v76, v201, v104
	v_fma_f32 v105, -v100, v201, v105
	v_fma_f32 v104, -v77, v202, v104
	v_fma_f32 v105, -v101, v202, v105
	v_fma_f32 v104, -v78, v203, v104
	v_fma_f32 v105, -v102, v203, v105
	v_fma_f32 v104, -v79, v204, v104
	v_fma_f32 v105, -v103, v204, v105
	ds_read_b128 v[72:75], v128 offset:53712
	ds_read_b128 v[76:79], v128 offset:53760
	s_waitcnt lgkmcnt(2)
	v_fma_f32 v104, -v208, v205, v104
	v_fma_f32 v105, -v212, v205, v105
	v_fma_f32 v104, -v209, v216, v104
	v_fma_f32 v105, -v213, v216, v105
	v_fma_f32 v104, -v210, v217, v104
	v_fma_f32 v105, -v214, v217, v105
	v_fma_f32 v219, -v211, v218, v104
	v_fma_f32 v105, -v215, v218, v105
	ds_read_b128 v[100:103], v128 offset:53888
	ds_read_b128 v[208:211], v128 offset:53776
	s_waitcnt lgkmcnt(3)
	v_fma_f32 v220, -v72, v219, v105
	ds_read_b128 v[212:215], v128 offset:53904
	ds_write2st64_b32 v133, v219, v220 offset0:20 offset1:21
	ds_read2st64_b32 v[80:81], v132 offset0:24 offset1:25
	s_waitcnt lgkmcnt(4)
	v_fma_f32 v130, -v76, v189, v130
	v_fma_f32 v131, -v100, v189, v131
	v_fma_f32 v130, -v77, v190, v130
	v_fma_f32 v131, -v101, v190, v131
	v_fma_f32 v130, -v78, v191, v130
	v_fma_f32 v131, -v102, v191, v131
	v_fma_f32 v130, -v79, v192, v130
	v_fma_f32 v131, -v103, v192, v131
	ds_read_b128 v[72:75], v128 offset:53792
	ds_read_b128 v[76:79], v128 offset:53920
	s_waitcnt lgkmcnt(4)
	v_fma_f32 v130, -v208, v193, v130
	v_fma_f32 v131, -v212, v193, v131
	v_fma_f32 v130, -v209, v194, v130
	v_fma_f32 v131, -v213, v194, v131
	v_fma_f32 v130, -v210, v195, v130
	v_fma_f32 v131, -v214, v195, v131
	v_fma_f32 v130, -v211, v196, v130
	v_fma_f32 v131, -v215, v196, v131
	ds_read_b128 v[100:103], v128 offset:53808
	ds_read_b128 v[208:211], v128 offset:53936
	s_waitcnt lgkmcnt(2)
	v_fma_f32 v130, -v72, v197, v130
	v_fma_f32 v131, -v76, v197, v131
	v_fma_f32 v130, -v73, v198, v130
	v_fma_f32 v131, -v77, v198, v131
	v_fma_f32 v130, -v74, v199, v130
	v_fma_f32 v131, -v78, v199, v131
	v_fma_f32 v130, -v75, v200, v130
	v_fma_f32 v131, -v79, v200, v131
	ds_read_b128 v[212:215], v128 offset:53824
	ds_read_b128 v[72:75], v128 offset:53952
	s_waitcnt lgkmcnt(2)
	v_fma_f32 v130, -v100, v201, v130
	v_fma_f32 v131, -v208, v201, v131
	v_fma_f32 v130, -v101, v202, v130
	v_fma_f32 v131, -v209, v202, v131
	v_fma_f32 v130, -v102, v203, v130
	v_fma_f32 v131, -v210, v203, v131
	v_fma_f32 v130, -v103, v204, v130
	v_fma_f32 v131, -v211, v204, v131
	ds_read_b128 v[76:79], v128 offset:53840
	ds_read_b128 v[100:103], v128 offset:53968
	s_waitcnt lgkmcnt(2)
; #define LAS __attribute__((address_space(3)))
; DI void gdn_scan_block(LAS unsigned char* lds, int c, const float* P, const GdnPar& pr, float* ORAW, int tid, int lane, int wave) {
;     ...
;                 for (int tb8 = 0; tb8 < 4; ++tb8) {
;                     float acc[8];
; #pragma unroll
;                     for (int r = 0; r < 8; ++r) acc[r] = RH[(8 * tb8 + r) * 64 + rowi];
; #pragma unroll
;                     for (int jb = 0; jb < tb8; ++jb)
; #pragma unroll
;                         for (int r = 0; r < 8; ++r) { const f32x4 b0 = *(const LAS f32x4*)(BM + (8 * tb8 + r) * 32 + 8 * jb), b1 = *(const LAS f32x4*)(BM + (8 * tb8 + r) * 32 + 8 * jb + 4);
;                             acc[r] -= ((b0[0] * cc[8 * jb] + b0[1] * cc[8 * jb + 1]) + (b0[2] * cc[8 * jb + 2] + b0[3] * cc[8 * jb + 3])) + ((b1[0] * cc[8 * jb + 4] + b1[1] * cc[8 * jb + 5]) + (b1[2] * cc[8 * jb + 6] + b1[3] * cc[8 * jb + 7])); }
; #pragma unroll
;                     for (int rh = 0; rh < 2; ++rh) {
;                         f32x4 d0[4], d1[4];
; #pragma unroll
;                         for (int r = 0; r < 4; ++r) { d0[r] = *(const LAS f32x4*)(BM + (8 * tb8 + 4 * rh + r) * 32 + 8 * tb8); if (rh) d1[r] = *(const LAS f32x4*)(BM + (8 * tb8 + 4 * rh + r) * 32 + 8 * tb8 + 4); }
; #pragma unroll
;                         for (int r = 0; r < 4; ++r) { float av = acc[4 * rh + r];
; #pragma unroll
;                             for (int q = 0; q < 8; ++q) if (q < 4 * rh + r) av -= (q < 4 ? d0[r][q & 3] : d1[r][q & 3]) * cc[8 * tb8 + q];
;                             cc[8 * tb8 + 4 * rh + r] = av; CC[(8 * tb8 + 4 * rh + r) * 64 + rowi] = av; }
	v_fma_f32 v130, -v212, v205, v130
	v_fma_f32 v131, -v72, v205, v131
	v_fma_f32 v130, -v213, v216, v130
	v_fma_f32 v131, -v73, v216, v131
	v_fma_f32 v130, -v214, v217, v130
	v_fma_f32 v131, -v74, v217, v131
	v_fma_f32 v130, -v215, v218, v130
	v_fma_f32 v131, -v75, v218, v131
	ds_read_b128 v[208:211], v128 offset:54016
	ds_read_b128 v[212:215], v128 offset:54144
	s_waitcnt lgkmcnt(2)
	v_fma_f32 v130, -v76, v219, v130
	v_fma_f32 v131, -v100, v219, v131
	v_fma_f32 v221, -v77, v220, v130
	v_fma_f32 v131, -v101, v220, v131
	v_fma_f32 v222, -v102, v221, v131
	ds_read_b128 v[72:75], v128 offset:54032
	ds_read_b128 v[76:79], v128 offset:54160
	ds_write2st64_b32 v133, v221, v222 offset0:22 offset1:23
	ds_read2st64_b32 v[104:105], v132 offset0:26 offset1:27
	s_waitcnt lgkmcnt(4)
	v_fma_f32 v80, -v208, v189, v80
	v_fma_f32 v81, -v212, v189, v81
	v_fma_f32 v80, -v209, v190, v80
	v_fma_f32 v81, -v213, v190, v81
	v_fma_f32 v80, -v210, v191, v80
	v_fma_f32 v81, -v214, v191, v81
	v_fma_f32 v80, -v211, v192, v80
	v_fma_f32 v81, -v215, v192, v81
	ds_read_b128 v[100:103], v128 offset:54048
	ds_read_b128 v[208:211], v128 offset:54176
	s_waitcnt lgkmcnt(4)
	v_fma_f32 v80, -v72, v193, v80
	v_fma_f32 v81, -v76, v193, v81
	v_fma_f32 v80, -v73, v194, v80
	v_fma_f32 v81, -v77, v194, v81
	v_fma_f32 v80, -v74, v195, v80
	v_fma_f32 v81, -v78, v195, v81
	v_fma_f32 v80, -v75, v196, v80
	v_fma_f32 v81, -v79, v196, v81
	ds_read_b128 v[212:215], v128 offset:54064
	ds_read_b128 v[72:75], v128 offset:54192
	s_waitcnt lgkmcnt(2)
	v_fma_f32 v80, -v100, v197, v80
	v_fma_f32 v81, -v208, v197, v81
	v_fma_f32 v80, -v101, v198, v80
	v_fma_f32 v81, -v209, v198, v81
	v_fma_f32 v80, -v102, v199, v80
	v_fma_f32 v81, -v210, v199, v81
	v_fma_f32 v80, -v103, v200, v80
	v_fma_f32 v81, -v211, v200, v81
	ds_read_b128 v[76:79], v128 offset:54080
	ds_read_b128 v[100:103], v128 offset:54208
	s_waitcnt lgkmcnt(2)
	v_fma_f32 v80, -v212, v201, v80
	v_fma_f32 v81, -v72, v201, v81
	v_fma_f32 v80, -v213, v202, v80
	v_fma_f32 v81, -v73, v202, v81
	v_fma_f32 v80, -v214, v203, v80
	v_fma_f32 v81, -v74, v203, v81
	v_fma_f32 v80, -v215, v204, v80
	v_fma_f32 v81, -v75, v204, v81
	ds_read_b128 v[208:211], v128 offset:54096
	ds_read_b128 v[212:215], v128 offset:54224
	s_waitcnt lgkmcnt(2)
	v_fma_f32 v80, -v76, v205, v80
	v_fma_f32 v81, -v100, v205, v81
	v_fma_f32 v80, -v77, v216, v80
	v_fma_f32 v81, -v101, v216, v81
	v_fma_f32 v80, -v78, v217, v80
	v_fma_f32 v81, -v102, v217, v81
	v_fma_f32 v80, -v79, v218, v80
	v_fma_f32 v81, -v103, v218, v81
	ds_read_b128 v[72:75], v128 offset:54240
	ds_read_b128 v[76:79], v128 offset:54272
	s_waitcnt lgkmcnt(2)
	v_fma_f32 v80, -v208, v219, v80
	v_fma_f32 v81, -v212, v219, v81
	v_fma_f32 v80, -v209, v220, v80
	v_fma_f32 v81, -v213, v220, v81
	v_fma_f32 v80, -v210, v221, v80
	v_fma_f32 v81, -v214, v221, v81
	v_fma_f32 v223, -v211, v222, v80
	v_fma_f32 v81, -v215, v222, v81
	ds_read_b128 v[100:103], v128 offset:54400
	ds_read_b128 v[208:211], v128 offset:54288
	s_waitcnt lgkmcnt(3)
	v_fma_f32 v224, -v72, v223, v81
	ds_read_b128 v[212:215], v128 offset:54416
	ds_write2st64_b32 v133, v223, v224 offset0:24 offset1:25
	ds_read2st64_b32 v[130:131], v132 offset0:28 offset1:29
	s_waitcnt lgkmcnt(4)
	v_fma_f32 v104, -v76, v189, v104
	v_fma_f32 v105, -v100, v189, v105
	v_fma_f32 v104, -v77, v190, v104
	v_fma_f32 v105, -v101, v190, v105
	v_fma_f32 v104, -v78, v191, v104
	v_fma_f32 v105, -v102, v191, v105
	v_fma_f32 v104, -v79, v192, v104
	v_fma_f32 v105, -v103, v192, v105
	ds_read_b128 v[72:75], v128 offset:54304
	ds_read_b128 v[76:79], v128 offset:54432
	s_waitcnt lgkmcnt(4)
	v_fma_f32 v104, -v208, v193, v104
	v_fma_f32 v105, -v212, v193, v105
	v_fma_f32 v104, -v209, v194, v104
	v_fma_f32 v105, -v213, v194, v105
	v_fma_f32 v104, -v210, v195, v104
	v_fma_f32 v105, -v214, v195, v105
	v_fma_f32 v104, -v211, v196, v104
	v_fma_f32 v105, -v215, v196, v105
	ds_read_b128 v[100:103], v128 offset:54320
	ds_read_b128 v[208:211], v128 offset:54448
	s_waitcnt lgkmcnt(2)
	v_fma_f32 v104, -v72, v197, v104
	v_fma_f32 v105, -v76, v197, v105
	v_fma_f32 v104, -v73, v198, v104
	v_fma_f32 v105, -v77, v198, v105
	v_fma_f32 v104, -v74, v199, v104
	v_fma_f32 v105, -v78, v199, v105
	v_fma_f32 v104, -v75, v200, v104
	v_fma_f32 v105, -v79, v200, v105
	ds_read_b128 v[212:215], v128 offset:54336
	ds_read_b128 v[72:75], v128 offset:54464
	s_waitcnt lgkmcnt(2)
	v_fma_f32 v104, -v100, v201, v104
	v_fma_f32 v105, -v208, v201, v105
	v_fma_f32 v104, -v101, v202, v104
	v_fma_f32 v105, -v209, v202, v105
	v_fma_f32 v104, -v102, v203, v104
	v_fma_f32 v105, -v210, v203, v105
	v_fma_f32 v104, -v103, v204, v104
	v_fma_f32 v105, -v211, v204, v105
	ds_read_b128 v[76:79], v128 offset:54352
	ds_read_b128 v[100:103], v128 offset:54480
	s_waitcnt lgkmcnt(2)
	v_fma_f32 v104, -v212, v205, v104
	v_fma_f32 v105, -v72, v205, v105
	v_fma_f32 v104, -v213, v216, v104
	v_fma_f32 v105, -v73, v216, v105
	v_fma_f32 v104, -v214, v217, v104
	v_fma_f32 v105, -v74, v217, v105
	v_fma_f32 v104, -v215, v218, v104
	v_fma_f32 v105, -v75, v218, v105
	ds_read_b128 v[208:211], v128 offset:54368
	ds_read_b128 v[212:215], v128 offset:54496
	s_waitcnt lgkmcnt(2)
	v_fma_f32 v104, -v76, v219, v104
	v_fma_f32 v105, -v100, v219, v105
	v_fma_f32 v104, -v77, v220, v104
	v_fma_f32 v105, -v101, v220, v105
	v_fma_f32 v104, -v78, v221, v104
	v_fma_f32 v105, -v102, v221, v105
	v_fma_f32 v104, -v79, v222, v104
	v_fma_f32 v105, -v103, v222, v105
	ds_read_b128 v[72:75], v128 offset:54528
	ds_read_b128 v[76:79], v128 offset:54656
	s_waitcnt lgkmcnt(2)
; #define LAS __attribute__((address_space(3)))
; DI void gdn_scan_block(LAS unsigned char* lds, int c, const float* P, const GdnPar& pr, float* ORAW, int tid, int lane, int wave) {
;     ...
;                 for (int tb8 = 0; tb8 < 4; ++tb8) {
;                     float acc[8];
; #pragma unroll
;                     for (int r = 0; r < 8; ++r) acc[r] = RH[(8 * tb8 + r) * 64 + rowi];
; #pragma unroll
;                     for (int jb = 0; jb < tb8; ++jb)
; #pragma unroll
;                         for (int r = 0; r < 8; ++r) { const f32x4 b0 = *(const LAS f32x4*)(BM + (8 * tb8 + r) * 32 + 8 * jb), b1 = *(const LAS f32x4*)(BM + (8 * tb8 + r) * 32 + 8 * jb + 4);
;                             acc[r] -= ((b0[0] * cc[8 * jb] + b0[1] * cc[8 * jb + 1]) + (b0[2] * cc[8 * jb + 2] + b0[3] * cc[8 * jb + 3])) + ((b1[0] * cc[8 * jb + 4] + b1[1] * cc[8 * jb + 5]) + (b1[2] * cc[8 * jb + 6] + b1[3] * cc[8 * jb + 7])); }
; #pragma unroll
;                     for (int rh = 0; rh < 2; ++rh) {
;                         f32x4 d0[4], d1[4];
; #pragma unroll
;                         for (int r = 0; r < 4; ++r) { d0[r] = *(const LAS f32x4*)(BM + (8 * tb8 + 4 * rh + r) * 32 + 8 * tb8); if (rh) d1[r] = *(const LAS f32x4*)(BM + (8 * tb8 + 4 * rh + r) * 32 + 8 * tb8 + 4); }
; #pragma unroll
;                         for (int r = 0; r < 4; ++r) { float av = acc[4 * rh + r];
; #pragma unroll
;                             for (int q = 0; q < 8; ++q) if (q < 4 * rh + r) av -= (q < 4 ? d0[r][q & 3] : d1[r][q & 3]) * cc[8 * tb8 + q];
;                             cc[8 * tb8 + 4 * rh + r] = av; CC[(8 * tb8 + 4 * rh + r) * 64 + rowi] = av; }
;                     }
;                 }
;             }
	v_fma_f32 v104, -v208, v223, v104
	v_fma_f32 v105, -v212, v223, v105
	v_fma_f32 v225, -v209, v224, v104
	v_fma_f32 v105, -v213, v224, v105
	v_fma_f32 v226, -v214, v225, v105
	ds_read_b128 v[100:103], v128 offset:54544
	ds_read_b128 v[208:211], v128 offset:54672
	ds_write2st64_b32 v133, v225, v226 offset0:26 offset1:27
	ds_read2st64_b32 v[80:81], v132 offset0:30 offset1:31
	s_waitcnt lgkmcnt(4)
	v_fma_f32 v130, -v72, v189, v130
	v_fma_f32 v131, -v76, v189, v131
	v_fma_f32 v130, -v73, v190, v130
	v_fma_f32 v131, -v77, v190, v131
	v_fma_f32 v130, -v74, v191, v130
	v_fma_f32 v131, -v78, v191, v131
	v_fma_f32 v130, -v75, v192, v130
	v_fma_f32 v131, -v79, v192, v131
	ds_read_b128 v[212:215], v128 offset:54560
	ds_read_b128 v[72:75], v128 offset:54688
	s_waitcnt lgkmcnt(4)
	v_fma_f32 v130, -v100, v193, v130
	v_fma_f32 v131, -v208, v193, v131
	v_fma_f32 v130, -v101, v194, v130
	v_fma_f32 v131, -v209, v194, v131
	v_fma_f32 v130, -v102, v195, v130
	v_fma_f32 v131, -v210, v195, v131
	v_fma_f32 v130, -v103, v196, v130
	v_fma_f32 v131, -v211, v196, v131
	ds_read_b128 v[76:79], v128 offset:54576
	ds_read_b128 v[100:103], v128 offset:54704
	s_waitcnt lgkmcnt(2)
	v_fma_f32 v130, -v212, v197, v130
	v_fma_f32 v131, -v72, v197, v131
	v_fma_f32 v130, -v213, v198, v130
	v_fma_f32 v131, -v73, v198, v131
	v_fma_f32 v130, -v214, v199, v130
	v_fma_f32 v131, -v74, v199, v131
	v_fma_f32 v130, -v215, v200, v130
	v_fma_f32 v131, -v75, v200, v131
	ds_read_b128 v[208:211], v128 offset:54592
	ds_read_b128 v[212:215], v128 offset:54720
	s_waitcnt lgkmcnt(2)
	v_fma_f32 v130, -v76, v201, v130
	v_fma_f32 v131, -v100, v201, v131
	v_fma_f32 v130, -v77, v202, v130
	v_fma_f32 v131, -v101, v202, v131
	v_fma_f32 v130, -v78, v203, v130
	v_fma_f32 v131, -v102, v203, v131
	v_fma_f32 v130, -v79, v204, v130
	v_fma_f32 v131, -v103, v204, v131
	ds_read_b128 v[72:75], v128 offset:54608
	ds_read_b128 v[76:79], v128 offset:54736
	s_waitcnt lgkmcnt(2)
	v_fma_f32 v130, -v208, v205, v130
	v_fma_f32 v131, -v212, v205, v131
	v_fma_f32 v130, -v209, v216, v130
	v_fma_f32 v131, -v213, v216, v131
	v_fma_f32 v130, -v210, v217, v130
	v_fma_f32 v131, -v214, v217, v131
	v_fma_f32 v130, -v211, v218, v130
	v_fma_f32 v131, -v215, v218, v131
	ds_read_b128 v[100:103], v128 offset:54624
	ds_read_b128 v[208:211], v128 offset:54752
	s_waitcnt lgkmcnt(2)
	v_fma_f32 v130, -v72, v219, v130
	v_fma_f32 v131, -v76, v219, v131
	v_fma_f32 v130, -v73, v220, v130
	v_fma_f32 v131, -v77, v220, v131
	v_fma_f32 v130, -v74, v221, v130
	v_fma_f32 v131, -v78, v221, v131
	v_fma_f32 v130, -v75, v222, v130
	v_fma_f32 v131, -v79, v222, v131
	ds_read_b128 v[212:215], v128 offset:54768
	ds_read_b128 v[72:75], v128 offset:54784
	s_waitcnt lgkmcnt(2)
	v_fma_f32 v130, -v100, v223, v130
	v_fma_f32 v131, -v208, v223, v131
	v_fma_f32 v130, -v101, v224, v130
	v_fma_f32 v131, -v209, v224, v131
	v_fma_f32 v130, -v102, v225, v130
	v_fma_f32 v131, -v210, v225, v131
	v_fma_f32 v227, -v103, v226, v130
	v_fma_f32 v131, -v211, v226, v131
	ds_read_b128 v[76:79], v128 offset:54912
	ds_read_b128 v[100:103], v128 offset:54800
	s_waitcnt lgkmcnt(3)
	v_fma_f32 v228, -v212, v227, v131
	ds_read_b128 v[208:211], v128 offset:54928
	ds_write2st64_b32 v133, v227, v228 offset0:28 offset1:29
	s_waitcnt lgkmcnt(3)
	v_fma_f32 v80, -v72, v189, v80
	v_fma_f32 v81, -v76, v189, v81
	v_fma_f32 v80, -v73, v190, v80
	v_fma_f32 v81, -v77, v190, v81
	v_fma_f32 v80, -v74, v191, v80
	v_fma_f32 v81, -v78, v191, v81
	v_fma_f32 v80, -v75, v192, v80
	v_fma_f32 v81, -v79, v192, v81
	ds_read_b128 v[212:215], v128 offset:54816
	ds_read_b128 v[72:75], v128 offset:54944
	s_waitcnt lgkmcnt(3)
	v_fma_f32 v80, -v100, v193, v80
	v_fma_f32 v81, -v208, v193, v81
	v_fma_f32 v80, -v101, v194, v80
	v_fma_f32 v81, -v209, v194, v81
	v_fma_f32 v80, -v102, v195, v80
	v_fma_f32 v81, -v210, v195, v81
	v_fma_f32 v80, -v103, v196, v80
	v_fma_f32 v81, -v211, v196, v81
	ds_read_b128 v[76:79], v128 offset:54832
	ds_read_b128 v[100:103], v128 offset:54960
	s_waitcnt lgkmcnt(2)
	v_fma_f32 v80, -v212, v197, v80
	v_fma_f32 v81, -v72, v197, v81
	v_fma_f32 v80, -v213, v198, v80
	v_fma_f32 v81, -v73, v198, v81
	v_fma_f32 v80, -v214, v199, v80
	v_fma_f32 v81, -v74, v199, v81
	v_fma_f32 v80, -v215, v200, v80
	v_fma_f32 v81, -v75, v200, v81
	ds_read_b128 v[208:211], v128 offset:54848
	ds_read_b128 v[212:215], v128 offset:54976
	s_waitcnt lgkmcnt(2)
	v_fma_f32 v80, -v76, v201, v80
	v_fma_f32 v81, -v100, v201, v81
	v_fma_f32 v80, -v77, v202, v80
	v_fma_f32 v81, -v101, v202, v81
	v_fma_f32 v80, -v78, v203, v80
	v_fma_f32 v81, -v102, v203, v81
	v_fma_f32 v80, -v79, v204, v80
	v_fma_f32 v81, -v103, v204, v81
	ds_read_b128 v[72:75], v128 offset:54864
	ds_read_b128 v[76:79], v128 offset:54992
	s_waitcnt lgkmcnt(2)
	v_fma_f32 v80, -v208, v205, v80
	v_fma_f32 v81, -v212, v205, v81
	v_fma_f32 v80, -v209, v216, v80
	v_fma_f32 v81, -v213, v216, v81
	v_fma_f32 v80, -v210, v217, v80
	v_fma_f32 v81, -v214, v217, v81
	v_fma_f32 v80, -v211, v218, v80
	v_fma_f32 v81, -v215, v218, v81
	ds_read_b128 v[100:103], v128 offset:54880
	ds_read_b128 v[208:211], v128 offset:55008
	s_waitcnt lgkmcnt(2)
	v_fma_f32 v80, -v72, v219, v80
	v_fma_f32 v81, -v76, v219, v81
	v_fma_f32 v80, -v73, v220, v80
	v_fma_f32 v81, -v77, v220, v81
	v_fma_f32 v80, -v74, v221, v80
	v_fma_f32 v81, -v78, v221, v81
	v_fma_f32 v80, -v75, v222, v80
	v_fma_f32 v81, -v79, v222, v81
	ds_read_b128 v[212:215], v128 offset:54896
	ds_read_b128 v[72:75], v128 offset:55024
	s_waitcnt lgkmcnt(2)
	v_fma_f32 v80, -v100, v223, v80
	v_fma_f32 v81, -v208, v223, v81
	v_fma_f32 v80, -v101, v224, v80
	v_fma_f32 v81, -v209, v224, v81
	v_fma_f32 v80, -v102, v225, v80
	v_fma_f32 v81, -v210, v225, v81
	v_fma_f32 v80, -v103, v226, v80
	v_fma_f32 v81, -v211, v226, v81
	s_waitcnt lgkmcnt(0)
	v_fma_f32 v80, -v212, v227, v80
	v_fma_f32 v81, -v72, v227, v81
	v_fma_f32 v229, -v213, v228, v80
	v_fma_f32 v81, -v73, v228, v81
	v_fma_f32 v106, -v74, v229, v81
	ds_write2st64_b32 v133, v229, v106 offset0:30 offset1:31
	s_branch .LBB0_888
